# plus: W_out and down epilogues issue their row loads together (counted waits); SGU loads issued together, weight fragments loaded once per phase
# speedup vs baseline: 1.0118x; 1.0118x over previous
.LBB0_224:
	s_mov_b64 s[16:17], s[60:61]
	s_cmpk_gt_i32 s42, 0x9ff
	s_cbranch_scc1 .LBB0_231
	s_load_dwordx2 s[24:25], s[16:17], 0xb0
	s_nop 0
	s_load_dwordx2 s[16:17], s[16:17], 0x48
	v_ashrrev_i32_e32 v24, 3, v0
	v_add_u32_e32 v6, 0x200, v0
	v_ashrrev_i32_e32 v25, 31, v24
	s_waitcnt lgkmcnt(0)
	s_add_u32 s38, s24, 0x18000000
	s_addc_u32 s39, s25, 0
	s_ashr_i32 s44, s19, 6
	s_lshl_b32 s46, s65, 11
	v_readlane_b32 s19, v255, 17
	s_add_u32 s40, s24, s19
	s_addc_u32 s41, s25, 0
	s_ashr_i32 s36, s42, 7
	s_ashr_i32 s37, s36, 31
	s_lshl_b32 s43, s42, 5
	s_lshl_b64 s[36:37], s[36:37], 12
	s_and_b32 s19, s43, 0xf80
	s_or_b32 s36, s36, s19
	v_ashrrev_i32_e32 v26, 3, v6
	v_lshl_add_u64 v[4:5], s[36:37], 0, v[24:25]
	v_ashrrev_i32_e32 v27, 31, v26
	v_lshlrev_b32_e32 v2, 3, v0
	v_lshlrev_b64 v[4:5], 12, v[4:5]
	s_lshl_b32 s19, s42, 7
	v_lshl_add_u64 v[6:7], s[36:37], 0, v[26:27]
	v_and_b32_e32 v2, 56, v2
	v_lshl_add_u64 v[4:5], s[38:39], 0, v[4:5]
	s_and_b32 s74, s19, 0x180
	v_lshlrev_b64 v[6:7], 12, v[6:7]
	v_lshl_add_u64 v[4:5], v[4:5], 0, s[74:75]
	v_lshlrev_b32_e32 v188, 1, v2
	v_lshl_add_u64 v[6:7], s[38:39], 0, v[6:7]
	v_lshl_add_u64 v[4:5], v[4:5], 0, v[188:189]
	v_lshl_add_u64 v[6:7], v[6:7], 0, s[74:75]
	v_lshl_add_u64 v[6:7], v[6:7], 0, v[188:189]
	global_load_dwordx4 v[16:19], v[4:5], off offset:3584
	global_load_dwordx4 v[20:23], v[6:7], off offset:3584
	s_lshl_b32 s37, s44, 4
	s_lshl_b32 s44, s44, 5
	s_and_b32 s19, s37, 0xffffffe0
	s_and_b32 s47, s44, 32
	s_ashr_i32 s36, s19, 31
	s_lshl_b32 s44, s47, 1
	v_and_b32_e32 v9, 31, v0
	s_add_u32 s44, s38, s44
	v_bfe_u32 v8, v0, 5, 1
	s_addc_u32 s45, s39, 0
	v_lshlrev_b32_e32 v188, 1, v9
	v_lshl_add_u64 v[30:31], s[44:45], 0, v[188:189]
	v_mov_b32_e32 v4, s37
	s_movk_i32 s37, 0xffe0
	v_lshlrev_b32_e32 v188, 4, v8
	v_bfi_b32 v29, s37, v4, v0
	v_lshl_add_u64 v[4:5], s[40:41], 0, v[188:189]
	s_mov_b64 s[40:41], 0x200000
	v_lshl_add_u64 v[32:33], v[4:5], 0, s[40:41]
	v_lshlrev_b32_e32 v4, 2, v0
	v_and_b32_e32 v1, 16, v0
	v_and_b32_e32 v4, 12, v4
	v_or3_b32 v1, v4, v1, s47
	v_or_b32_e32 v4, s47, v9
	v_lshlrev_b32_e32 v188, 1, v4
	v_lshlrev_b32_e32 v28, 2, v8
	v_lshl_add_u64 v[4:5], s[24:25], 0, v[188:189]
	s_mov_b64 s[24:25], 0x2c000600
	v_bfe_u32 v3, v0, 2, 2
	s_add_u32 s16, s16, s46
	v_or_b32_e32 v34, s19, v28
	v_lshl_add_u64 v[36:37], v[4:5], 0, s[24:25]
	s_movk_i32 s24, 0x90
	v_lshl_or_b32 v3, v8, 3, v3
	s_addc_u32 s17, s17, 0
	v_ashrrev_i32_e32 v35, 31, v34
	v_mul_lo_u32 v4, v24, s24
	v_lshlrev_b32_e32 v0, 4, v0
	v_mul_lo_u32 v5, v26, s24
	v_lshlrev_b32_e32 v1, 1, v1
	v_mad_u32_u24 v3, v3, s24, 0
	v_or_b32_e32 v68, 1, v34
	v_or_b32_e32 v70, 2, v34
	v_or_b32_e32 v72, 3, v34
	v_or_b32_e32 v74, 8, v34
	v_or_b32_e32 v76, 9, v34
	v_or_b32_e32 v78, 10, v34
	v_or_b32_e32 v80, 11, v34
	v_or_b32_e32 v82, 16, v34
	v_or_b32_e32 v84, 17, v34
	v_or_b32_e32 v86, 18, v34
	v_or_b32_e32 v88, 19, v34
	v_or_b32_e32 v90, 24, v34
	v_or_b32_e32 v92, 25, v34
	v_or_b32_e32 v94, 26, v34
	v_or_b32_e32 v96, 27, v34
	v_add_u32_e32 v4, 0, v4
	v_and_b32_e32 v0, 0x70, v0
	v_add_u32_e32 v5, 0, v5
	v_lshl_add_u64 v[98:99], v[34:35], 2, s[16:17]
	s_add_i32 s16, s3, s42
	v_or_b32_e32 v38, 1, v28
	v_or_b32_e32 v40, 2, v28
	v_or_b32_e32 v42, 3, v28
	v_or_b32_e32 v44, 8, v28
	v_or_b32_e32 v46, 9, v28
	v_or_b32_e32 v48, 10, v28
	v_or_b32_e32 v50, 11, v28
	v_or_b32_e32 v52, 16, v28
	v_or_b32_e32 v54, 17, v28
	v_or_b32_e32 v56, 18, v28
	v_or_b32_e32 v58, 19, v28
	v_or_b32_e32 v60, 24, v28
	v_or_b32_e32 v62, 25, v28
	v_or_b32_e32 v64, 26, v28
	v_or_b32_e32 v66, 27, v28
	v_ashrrev_i32_e32 v69, 31, v68
	v_ashrrev_i32_e32 v71, 31, v70
	v_ashrrev_i32_e32 v73, 31, v72
	v_ashrrev_i32_e32 v75, 31, v74
	v_ashrrev_i32_e32 v77, 31, v76
	v_ashrrev_i32_e32 v79, 31, v78
	v_ashrrev_i32_e32 v81, 31, v80
	v_ashrrev_i32_e32 v83, 31, v82
	v_ashrrev_i32_e32 v85, 31, v84
	v_ashrrev_i32_e32 v87, 31, v86
	v_ashrrev_i32_e32 v89, 31, v88
	v_ashrrev_i32_e32 v91, 31, v90
	v_ashrrev_i32_e32 v93, 31, v92
	v_ashrrev_i32_e32 v95, 31, v94
	v_ashrrev_i32_e32 v97, 31, v96
	s_lshl_b32 s24, s3, 5
	s_lshl_b32 s25, s16, 6
	s_lshl_b32 s37, s3, 6
	v_add_u32_e32 v39, v4, v0
	v_add_u32_e32 v41, v5, v0
	v_lshlrev_b32_e32 v188, 1, v2
	v_add_u32_e32 v43, v3, v1
	s_and_b32 s16, s42, 3
	s_lshl_b32 s74, s16, 7
	v_add_u32_e32 v140, s74, v29
	v_ashrrev_i32_e32 v141, 31, v140
	v_lshlrev_b64 v[140:141], 8, v[140:141]
	v_lshl_add_u64 v[140:141], v[32:33], 0, v[140:141]
	global_load_dwordx4 v[142:145], v[140:141], off
	global_load_dwordx4 v[146:149], v[140:141], off offset:32
	global_load_dwordx4 v[150:153], v[140:141], off offset:64
	global_load_dwordx4 v[154:157], v[140:141], off offset:96
	global_load_dwordx4 v[158:161], v[140:141], off offset:128
	global_load_dwordx4 v[162:165], v[140:141], off offset:160
	global_load_dwordx4 v[166:169], v[140:141], off offset:192
	global_load_dwordx4 v[170:173], v[140:141], off offset:224
	s_branch .LBB0_227
.LBB0_226:
	s_ashr_i32 s46, s42, 7
	s_ashr_i32 s47, s46, 31
	s_and_b32 s17, s43, 0xf80
	s_and_b32 s16, s42, 3
	s_lshl_b64 s[42:43], s[46:47], 12
	s_or_b32 s42, s42, s17
	s_add_u32 s17, s42, s19
	s_addc_u32 s46, s43, s36
	s_lshl_b32 s74, s16, 7
	v_mov_b32_e32 v3, s46
	v_or_b32_e32 v2, s17, v28
	v_lshl_add_u64 v[0:1], v[30:31], 0, s[74:75]
	v_lshlrev_b64 v[2:3], 12, v[2:3]
	v_lshl_add_u64 v[102:103], v[0:1], 0, v[2:3]
	v_mov_b32_e32 v3, s46
	v_or_b32_e32 v2, s17, v38
	v_lshlrev_b64 v[2:3], 12, v[2:3]
	v_lshl_add_u64 v[104:105], v[0:1], 0, v[2:3]
	v_mov_b32_e32 v3, s46
	v_or_b32_e32 v2, s17, v40
	v_lshlrev_b64 v[2:3], 12, v[2:3]
	v_lshl_add_u64 v[106:107], v[0:1], 0, v[2:3]
	v_mov_b32_e32 v3, s46
	v_or_b32_e32 v2, s17, v42
	v_lshlrev_b64 v[2:3], 12, v[2:3]
	v_lshl_add_u64 v[108:109], v[0:1], 0, v[2:3]
	v_mov_b32_e32 v3, s46
	v_or_b32_e32 v2, s17, v44
	v_lshlrev_b64 v[2:3], 12, v[2:3]
	v_lshl_add_u64 v[110:111], v[0:1], 0, v[2:3]
	v_mov_b32_e32 v3, s46
	v_or_b32_e32 v2, s17, v46
	v_lshlrev_b64 v[2:3], 12, v[2:3]
	v_lshl_add_u64 v[112:113], v[0:1], 0, v[2:3]
	v_mov_b32_e32 v3, s46
	v_or_b32_e32 v2, s17, v48
	v_lshlrev_b64 v[2:3], 12, v[2:3]
	v_lshl_add_u64 v[114:115], v[0:1], 0, v[2:3]
	v_mov_b32_e32 v3, s46
	v_or_b32_e32 v2, s17, v50
	v_lshlrev_b64 v[2:3], 12, v[2:3]
	v_lshl_add_u64 v[116:117], v[0:1], 0, v[2:3]
	v_mov_b32_e32 v3, s46
	v_or_b32_e32 v2, s17, v52
	v_lshlrev_b64 v[2:3], 12, v[2:3]
	v_lshl_add_u64 v[118:119], v[0:1], 0, v[2:3]
	v_mov_b32_e32 v3, s46
	v_or_b32_e32 v2, s17, v54
	v_lshlrev_b64 v[2:3], 12, v[2:3]
	v_lshl_add_u64 v[120:121], v[0:1], 0, v[2:3]
	v_mov_b32_e32 v3, s46
	v_or_b32_e32 v2, s17, v56
	v_lshlrev_b64 v[2:3], 12, v[2:3]
	v_lshl_add_u64 v[122:123], v[0:1], 0, v[2:3]
	v_mov_b32_e32 v3, s46
	v_or_b32_e32 v2, s17, v58
	v_lshlrev_b64 v[2:3], 12, v[2:3]
	v_lshl_add_u64 v[124:125], v[0:1], 0, v[2:3]
	v_mov_b32_e32 v3, s46
	v_or_b32_e32 v2, s17, v60
	v_lshlrev_b64 v[2:3], 12, v[2:3]
	v_lshl_add_u64 v[126:127], v[0:1], 0, v[2:3]
	v_mov_b32_e32 v3, s46
	v_or_b32_e32 v2, s17, v62
	v_lshlrev_b64 v[2:3], 12, v[2:3]
	v_lshl_add_u64 v[128:129], v[0:1], 0, v[2:3]
	v_mov_b32_e32 v3, s46
	v_or_b32_e32 v2, s17, v64
	v_lshlrev_b64 v[2:3], 12, v[2:3]
	v_lshl_add_u64 v[130:131], v[0:1], 0, v[2:3]
	v_mov_b32_e32 v3, s46
	v_or_b32_e32 v2, s17, v66
	v_lshlrev_b64 v[2:3], 12, v[2:3]
	v_lshl_add_u64 v[132:133], v[0:1], 0, v[2:3]
	v_add_u32_e32 v0, s74, v29
	v_ashrrev_i32_e32 v1, 31, v0
	v_lshlrev_b64 v[0:1], 8, v[0:1]
	v_lshl_add_u64 v[100:101], v[32:33], 0, v[0:1]
	global_load_ushort v45, v[102:103], off offset:3072
	v_lshl_add_u64 v[100:101], v[36:37], 0, s[74:75]
	s_lshl_b32 s74, s16, 9
	v_lshl_add_u64 v[102:103], v[98:99], 0, s[74:75]
	global_load_dwordx4 v[228:231], v[102:103], off
	global_load_dwordx4 v[232:235], v[102:103], off offset:32
	global_load_dwordx4 v[236:239], v[102:103], off offset:64
	global_load_dwordx4 v[240:243], v[102:103], off offset:96
	global_load_ushort v47, v[104:105], off offset:3072
	global_load_ushort v49, v[106:107], off offset:3072
	global_load_ushort v51, v[108:109], off offset:3072
	global_load_ushort v53, v[110:111], off offset:3072
	global_load_ushort v55, v[112:113], off offset:3072
	global_load_ushort v57, v[114:115], off offset:3072
	global_load_ushort v59, v[116:117], off offset:3072
	global_load_ushort v61, v[118:119], off offset:3072
	global_load_ushort v63, v[120:121], off offset:3072
	global_load_ushort v65, v[122:123], off offset:3072
	global_load_ushort v67, v[124:125], off offset:3072
	global_load_ushort v244, v[126:127], off offset:3072
	global_load_ushort v245, v[128:129], off offset:3072
	global_load_ushort v246, v[130:131], off offset:3072
	global_load_ushort v247, v[132:133], off offset:3072
	s_add_i32 s25, s25, s37
	s_and_b64 vcc, exec, s[40:41]
	s_cbranch_vccnz .Lsgu_nopf
	global_load_dwordx4 v[16:19], v[134:135], off offset:3584
	global_load_dwordx4 v[20:23], v[136:137], off offset:3584
.Lsgu_nopf:
	ds_read_b64_tr_b16 v[174:175], v43
	ds_read_b64_tr_b16 v[176:177], v43 offset:576
	ds_read_b64_tr_b16 v[178:179], v43 offset:2304
	ds_read_b64_tr_b16 v[180:181], v43 offset:2880
	ds_read_b64_tr_b16 v[182:183], v43 offset:4608
	ds_read_b64_tr_b16 v[184:185], v43 offset:5184
	ds_read_b64_tr_b16 v[194:195], v43 offset:6912
	ds_read_b64_tr_b16 v[196:197], v43 offset:7488
	ds_read_b64_tr_b16 v[198:199], v43 offset:9216
	ds_read_b64_tr_b16 v[200:201], v43 offset:9792
	ds_read_b64_tr_b16 v[202:203], v43 offset:11520
	ds_read_b64_tr_b16 v[204:205], v43 offset:12096
	ds_read_b64_tr_b16 v[206:207], v43 offset:13824
	ds_read_b64_tr_b16 v[208:209], v43 offset:14400
	ds_read_b64_tr_b16 v[210:211], v43 offset:16128
	ds_read_b64_tr_b16 v[212:213], v43 offset:16704
	s_waitcnt lgkmcnt(0)
	v_mfma_f32_32x32x16_bf16 v[0:15], v[142:145], v[174:177], 0
	v_mfma_f32_32x32x16_bf16 v[0:15], v[146:149], v[178:181], v[0:15]
	v_mfma_f32_32x32x16_bf16 v[0:15], v[150:153], v[182:185], v[0:15]
	v_mfma_f32_32x32x16_bf16 v[0:15], v[154:157], v[194:197], v[0:15]
	v_mfma_f32_32x32x16_bf16 v[0:15], v[158:161], v[198:201], v[0:15]
	v_mfma_f32_32x32x16_bf16 v[0:15], v[162:165], v[202:205], v[0:15]
	v_mfma_f32_32x32x16_bf16 v[0:15], v[166:169], v[206:209], v[0:15]
	v_mfma_f32_32x32x16_bf16 v[0:15], v[170:173], v[210:213], v[0:15]
	s_nop 11
	s_waitcnt vmcnt(15)
	v_lshlrev_b32_e32 v186, 16, v45
	v_add_f32_e32 v187, v0, v228
	v_mul_f32_e32 v187, v187, v186
	v_bfe_u32 v186, v187, 16, 1
	v_add3_u32 v187, v187, v186, s33
	v_lshl_add_u64 v[248:249], s[42:43], 0, v[34:35]
	v_lshlrev_b64 v[248:249], 11, v[248:249]
	v_lshl_add_u64 v[248:249], v[100:101], 0, v[248:249]
	global_store_short_d16_hi v[248:249], v187, off
	s_waitcnt vmcnt(15)
	v_lshlrev_b32_e32 v220, 16, v47
	v_add_f32_e32 v221, v1, v229
	v_mul_f32_e32 v221, v221, v220
	v_bfe_u32 v220, v221, 16, 1
	v_add3_u32 v221, v221, v220, s33
	v_lshl_add_u64 v[250:251], s[42:43], 0, v[68:69]
	v_lshlrev_b64 v[250:251], 11, v[250:251]
	v_lshl_add_u64 v[250:251], v[100:101], 0, v[250:251]
	global_store_short_d16_hi v[250:251], v221, off
	s_waitcnt vmcnt(15)
	v_lshlrev_b32_e32 v222, 16, v49
	v_add_f32_e32 v223, v2, v230
	v_mul_f32_e32 v223, v223, v222
	v_bfe_u32 v222, v223, 16, 1
	v_add3_u32 v223, v223, v222, s33
	v_lshl_add_u64 v[224:225], s[42:43], 0, v[70:71]
	v_lshlrev_b64 v[224:225], 11, v[224:225]
	v_lshl_add_u64 v[224:225], v[100:101], 0, v[224:225]
	global_store_short_d16_hi v[224:225], v223, off
	s_waitcnt vmcnt(15)
	v_lshlrev_b32_e32 v186, 16, v51
	v_add_f32_e32 v187, v3, v231
	v_mul_f32_e32 v187, v187, v186
	v_bfe_u32 v186, v187, 16, 1
	v_add3_u32 v187, v187, v186, s33
	v_lshl_add_u64 v[248:249], s[42:43], 0, v[72:73]
	v_lshlrev_b64 v[248:249], 11, v[248:249]
	v_lshl_add_u64 v[248:249], v[100:101], 0, v[248:249]
	global_store_short_d16_hi v[248:249], v187, off
	s_waitcnt vmcnt(15)
	v_lshlrev_b32_e32 v220, 16, v53
	v_add_f32_e32 v221, v4, v232
	v_mul_f32_e32 v221, v221, v220
	v_bfe_u32 v220, v221, 16, 1
	v_add3_u32 v221, v221, v220, s33
	v_lshl_add_u64 v[250:251], s[42:43], 0, v[74:75]
	v_lshlrev_b64 v[250:251], 11, v[250:251]
	v_lshl_add_u64 v[250:251], v[100:101], 0, v[250:251]
	global_store_short_d16_hi v[250:251], v221, off
	s_waitcnt vmcnt(15)
	v_lshlrev_b32_e32 v222, 16, v55
	v_add_f32_e32 v223, v5, v233
	v_mul_f32_e32 v223, v223, v222
	v_bfe_u32 v222, v223, 16, 1
	v_add3_u32 v223, v223, v222, s33
	v_lshl_add_u64 v[224:225], s[42:43], 0, v[76:77]
	v_lshlrev_b64 v[224:225], 11, v[224:225]
	v_lshl_add_u64 v[224:225], v[100:101], 0, v[224:225]
	global_store_short_d16_hi v[224:225], v223, off
	s_waitcnt vmcnt(15)
	v_lshlrev_b32_e32 v186, 16, v57
	v_add_f32_e32 v187, v6, v234
	v_mul_f32_e32 v187, v187, v186
	v_bfe_u32 v186, v187, 16, 1
	v_add3_u32 v187, v187, v186, s33
	v_lshl_add_u64 v[248:249], s[42:43], 0, v[78:79]
	v_lshlrev_b64 v[248:249], 11, v[248:249]
	v_lshl_add_u64 v[248:249], v[100:101], 0, v[248:249]
	global_store_short_d16_hi v[248:249], v187, off
	s_waitcnt vmcnt(15)
	v_lshlrev_b32_e32 v220, 16, v59
	v_add_f32_e32 v221, v7, v235
	v_mul_f32_e32 v221, v221, v220
	v_bfe_u32 v220, v221, 16, 1
	v_add3_u32 v221, v221, v220, s33
	v_lshl_add_u64 v[250:251], s[42:43], 0, v[80:81]
	v_lshlrev_b64 v[250:251], 11, v[250:251]
	v_lshl_add_u64 v[250:251], v[100:101], 0, v[250:251]
	global_store_short_d16_hi v[250:251], v221, off
	s_waitcnt vmcnt(15)
	v_lshlrev_b32_e32 v222, 16, v61
	v_add_f32_e32 v223, v8, v236
	v_mul_f32_e32 v223, v223, v222
	v_bfe_u32 v222, v223, 16, 1
	v_add3_u32 v223, v223, v222, s33
	v_lshl_add_u64 v[224:225], s[42:43], 0, v[82:83]
	v_lshlrev_b64 v[224:225], 11, v[224:225]
	v_lshl_add_u64 v[224:225], v[100:101], 0, v[224:225]
	global_store_short_d16_hi v[224:225], v223, off
	s_waitcnt vmcnt(15)
	v_lshlrev_b32_e32 v186, 16, v63
	v_add_f32_e32 v187, v9, v237
	v_mul_f32_e32 v187, v187, v186
	v_bfe_u32 v186, v187, 16, 1
	v_add3_u32 v187, v187, v186, s33
	v_lshl_add_u64 v[248:249], s[42:43], 0, v[84:85]
	v_lshlrev_b64 v[248:249], 11, v[248:249]
	v_lshl_add_u64 v[248:249], v[100:101], 0, v[248:249]
	global_store_short_d16_hi v[248:249], v187, off
	s_waitcnt vmcnt(15)
	v_lshlrev_b32_e32 v220, 16, v65
	v_add_f32_e32 v221, v10, v238
	v_mul_f32_e32 v221, v221, v220
	v_bfe_u32 v220, v221, 16, 1
	v_add3_u32 v221, v221, v220, s33
	v_lshl_add_u64 v[250:251], s[42:43], 0, v[86:87]
	v_lshlrev_b64 v[250:251], 11, v[250:251]
	v_lshl_add_u64 v[250:251], v[100:101], 0, v[250:251]
	global_store_short_d16_hi v[250:251], v221, off
	s_waitcnt vmcnt(15)
	v_lshlrev_b32_e32 v222, 16, v67
	v_add_f32_e32 v223, v11, v239
	v_mul_f32_e32 v223, v223, v222
	v_bfe_u32 v222, v223, 16, 1
	v_add3_u32 v223, v223, v222, s33
	v_lshl_add_u64 v[224:225], s[42:43], 0, v[88:89]
	v_lshlrev_b64 v[224:225], 11, v[224:225]
	v_lshl_add_u64 v[224:225], v[100:101], 0, v[224:225]
	global_store_short_d16_hi v[224:225], v223, off
	s_waitcnt vmcnt(15)
	v_lshlrev_b32_e32 v186, 16, v244
	v_add_f32_e32 v187, v12, v240
	v_mul_f32_e32 v187, v187, v186
	v_bfe_u32 v186, v187, 16, 1
	v_add3_u32 v187, v187, v186, s33
	v_lshl_add_u64 v[248:249], s[42:43], 0, v[90:91]
	v_lshlrev_b64 v[248:249], 11, v[248:249]
	v_lshl_add_u64 v[248:249], v[100:101], 0, v[248:249]
	global_store_short_d16_hi v[248:249], v187, off
	s_waitcnt vmcnt(15)
	v_lshlrev_b32_e32 v220, 16, v245
	v_add_f32_e32 v221, v13, v241
	v_mul_f32_e32 v221, v221, v220
	v_bfe_u32 v220, v221, 16, 1
	v_add3_u32 v221, v221, v220, s33
	v_lshl_add_u64 v[250:251], s[42:43], 0, v[92:93]
	v_lshlrev_b64 v[250:251], 11, v[250:251]
	v_lshl_add_u64 v[250:251], v[100:101], 0, v[250:251]
	global_store_short_d16_hi v[250:251], v221, off
	s_waitcnt vmcnt(15)
	v_lshlrev_b32_e32 v222, 16, v246
	v_add_f32_e32 v223, v14, v242
	v_mul_f32_e32 v223, v223, v222
	v_bfe_u32 v222, v223, 16, 1
	v_add3_u32 v223, v223, v222, s33
	v_lshl_add_u64 v[224:225], s[42:43], 0, v[94:95]
	v_lshlrev_b64 v[224:225], 11, v[224:225]
	v_lshl_add_u64 v[224:225], v[100:101], 0, v[224:225]
	global_store_short_d16_hi v[224:225], v223, off
	s_waitcnt vmcnt(15)
	v_lshlrev_b32_e32 v186, 16, v247
	v_add_f32_e32 v187, v15, v243
	v_mul_f32_e32 v187, v187, v186
	v_bfe_u32 v186, v187, 16, 1
	v_add3_u32 v187, v187, v186, s33
	v_lshl_add_u64 v[248:249], s[42:43], 0, v[96:97]
	v_lshlrev_b64 v[248:249], 11, v[248:249]
	v_lshl_add_u64 v[248:249], v[100:101], 0, v[248:249]
	s_mov_b32 s43, s45
	s_mov_b32 s42, s44
	global_store_short_d16_hi v[248:249], v187, off
	s_barrier
	s_cbranch_vccnz .LBB0_231

.LBB0_229:
	s_andn2_b64 vcc, exec, s[16:17]
	s_cbranch_vccnz .LBB0_226
	s_ashr_i32 s16, s44, 7
	s_ashr_i32 s17, s16, 31
	s_add_i32 s45, s24, s43
	s_lshl_b64 s[16:17], s[16:17], 12
	s_and_b32 s46, s45, 0xf80
	s_or_b32 s16, s16, s46
	v_lshl_add_u64 v[134:135], s[16:17], 0, v[24:25]
	s_and_b32 s46, s25, 0xc0
	v_lshlrev_b64 v[134:135], 12, v[134:135]
	v_lshl_add_u64 v[136:137], s[16:17], 0, v[26:27]
	v_lshl_add_u64 v[134:135], s[38:39], 0, v[134:135]
	s_lshl_b32 s74, s46, 1
	v_lshlrev_b64 v[136:137], 12, v[136:137]
	v_lshl_add_u64 v[134:135], v[134:135], 0, s[74:75]
	v_lshl_add_u64 v[136:137], s[38:39], 0, v[136:137]
	v_lshl_add_u64 v[134:135], v[134:135], 0, v[188:189]
	v_lshl_add_u64 v[136:137], v[136:137], 0, s[74:75]
	v_lshl_add_u64 v[136:137], v[136:137], 0, v[188:189]
	s_branch .LBB0_226

.LBB0_357:
	v_mov_b32_e32 v138, v142
	v_mov_b32_e32 v139, v143
	s_lshl_b32 s16, s76, 8
	s_add_i32 s16, s16, s66
	v_add_u32_e32 v138, s16, v138
	s_lshl_b32 s16, s74, 8
	s_or_b32 s16, s16, s67
	v_lshl_add_u32 v140, v139, 3, s16
	v_ashrrev_i32_e32 v139, 31, v138
	v_ashrrev_i32_e32 v141, 31, v140
	v_lshlrev_b64 v[138:139], 10, v[138:139]
	v_lshl_add_u64 v[138:139], v[138:139], 0, v[140:141]
	v_lshlrev_b64 v[138:139], 1, v[138:139]
	v_lshl_add_u64 v[228:229], s[40:41], 0, v[138:139]
	global_load_dwordx4 v[154:157], v[228:229], off nt
	global_load_dwordx4 v[158:161], v[228:229], off offset:256 nt
	s_mov_b64 s[16:17], 0x8000
	v_lshl_add_u64 v[230:231], v[138:139], 0, s[16:17]
	v_lshl_add_u64 v[230:231], s[40:41], 0, v[230:231]
	global_load_dwordx4 v[162:165], v[230:231], off nt
	global_load_dwordx4 v[166:169], v[230:231], off offset:256 nt
	s_mov_b64 s[16:17], 0x10000
	v_lshl_add_u64 v[232:233], v[138:139], 0, s[16:17]
	v_lshl_add_u64 v[232:233], s[40:41], 0, v[232:233]
	global_load_dwordx4 v[170:173], v[232:233], off nt
	global_load_dwordx4 v[174:177], v[232:233], off offset:256 nt
	s_mov_b64 s[16:17], 0x18000
	v_lshl_add_u64 v[234:235], v[138:139], 0, s[16:17]
	v_lshl_add_u64 v[234:235], s[40:41], 0, v[234:235]
	global_load_dwordx4 v[178:181], v[234:235], off nt
	global_load_dwordx4 v[182:185], v[234:235], off offset:256 nt
	v_lshl_add_u64 v[228:229], v[138:139], 0, s[26:27]
	v_lshl_add_u64 v[228:229], s[40:41], 0, v[228:229]
	global_load_dwordx4 v[194:197], v[228:229], off nt
	global_load_dwordx4 v[198:201], v[228:229], off offset:256 nt
	s_mov_b64 s[16:17], 0x48000
	v_lshl_add_u64 v[230:231], v[138:139], 0, s[16:17]
	v_lshl_add_u64 v[230:231], s[40:41], 0, v[230:231]
	global_load_dwordx4 v[202:205], v[230:231], off nt
	global_load_dwordx4 v[206:209], v[230:231], off offset:256 nt
	s_mov_b64 s[16:17], 0x50000
	v_lshl_add_u64 v[232:233], v[138:139], 0, s[16:17]
	v_lshl_add_u64 v[232:233], s[40:41], 0, v[232:233]
	global_load_dwordx4 v[210:213], v[232:233], off nt
	global_load_dwordx4 v[220:223], v[232:233], off offset:256 nt
	s_mov_b64 s[16:17], 0x58000
	v_lshl_add_u64 v[234:235], v[138:139], 0, s[16:17]
	v_lshl_add_u64 v[234:235], s[40:41], 0, v[234:235]
	global_load_dwordx4 v[236:239], v[234:235], off nt
	global_load_dwordx4 v[240:243], v[234:235], off offset:256 nt
	s_mov_b64 s[16:17], 0x8000
	s_andn2_b64 vcc, exec, s[38:39]
	s_mov_b64 s[82:83], 0x800
	s_waitcnt vmcnt(15)
	v_lshlrev_b32_e32 v150, 16, v154
	v_and_b32_e32 v151, 0xffff0000, v154
	v_lshlrev_b32_e32 v146, 16, v155
	v_and_b32_e32 v147, 0xffff0000, v155
	v_lshlrev_b32_e32 v152, 16, v156
	v_and_b32_e32 v153, 0xffff0000, v156
	v_lshlrev_b32_e32 v148, 16, v157
	v_and_b32_e32 v149, 0xffff0000, v157
	v_pk_fma_f32 v[126:127], v[146:147], s[18:19], v[126:127] op_sel_hi:[1,0,1]
	v_pk_fma_f32 v[124:125], v[150:151], s[18:19], v[124:125] op_sel_hi:[1,0,1]
	v_pk_fma_f32 v[146:147], v[148:149], s[18:19], v[122:123] op_sel_hi:[1,0,1]
	v_pk_fma_f32 v[122:123], v[152:153], s[18:19], v[120:121] op_sel_hi:[1,0,1]
	v_cvt_pk_bf16_f32 v120, v124, v125
	v_cvt_pk_bf16_f32 v121, v126, v127
	v_cvt_pk_bf16_f32 v122, v122, v123
	v_cvt_pk_bf16_f32 v123, v146, v147
	v_lshl_add_u64 v[124:125], s[42:43], 0, v[138:139]
	global_store_dwordx4 v[124:125], v[120:123], off
	s_waitcnt vmcnt(15)
	v_lshlrev_b32_e32 v126, 16, v158
	v_and_b32_e32 v127, 0xffff0000, v158
	v_lshlrev_b32_e32 v120, 16, v159
	v_and_b32_e32 v121, 0xffff0000, v159
	v_lshlrev_b32_e32 v140, 16, v160
	v_and_b32_e32 v141, 0xffff0000, v160
	v_lshlrev_b32_e32 v122, 16, v161
	v_and_b32_e32 v123, 0xffff0000, v161
	v_pk_fma_f32 v[118:119], v[120:121], s[18:19], v[118:119] op_sel_hi:[1,0,1]
	v_pk_fma_f32 v[116:117], v[126:127], s[18:19], v[116:117] op_sel_hi:[1,0,1]
	v_pk_fma_f32 v[120:121], v[122:123], s[18:19], v[114:115] op_sel_hi:[1,0,1]
	v_pk_fma_f32 v[114:115], v[140:141], s[18:19], v[112:113] op_sel_hi:[1,0,1]
	v_cvt_pk_bf16_f32 v112, v116, v117
	v_cvt_pk_bf16_f32 v113, v118, v119
	v_cvt_pk_bf16_f32 v114, v114, v115
	v_cvt_pk_bf16_f32 v115, v120, v121
	v_lshl_add_u64 v[116:117], v[138:139], 0, s[16:17]
	global_store_dwordx4 v[124:125], v[112:115], off offset:256
	s_mov_b64 s[16:17], 0x10000
	s_waitcnt vmcnt(15)
	v_lshlrev_b32_e32 v120, 16, v162
	v_and_b32_e32 v121, 0xffff0000, v162
	v_lshlrev_b32_e32 v112, 16, v163
	v_and_b32_e32 v113, 0xffff0000, v163
	v_lshlrev_b32_e32 v122, 16, v164
	v_and_b32_e32 v123, 0xffff0000, v164
	v_lshlrev_b32_e32 v114, 16, v165
	v_and_b32_e32 v115, 0xffff0000, v165
	v_pk_fma_f32 v[110:111], v[112:113], s[18:19], v[110:111] op_sel_hi:[1,0,1]
	v_pk_fma_f32 v[108:109], v[120:121], s[18:19], v[108:109] op_sel_hi:[1,0,1]
	v_pk_fma_f32 v[112:113], v[114:115], s[18:19], v[106:107] op_sel_hi:[1,0,1]
	v_pk_fma_f32 v[106:107], v[122:123], s[18:19], v[104:105] op_sel_hi:[1,0,1]
	v_cvt_pk_bf16_f32 v104, v108, v109
	v_cvt_pk_bf16_f32 v105, v110, v111
	v_cvt_pk_bf16_f32 v106, v106, v107
	v_cvt_pk_bf16_f32 v107, v112, v113
	v_lshl_add_u64 v[108:109], s[42:43], 0, v[116:117]
	global_store_dwordx4 v[108:109], v[104:107], off
	s_waitcnt vmcnt(15)
	v_lshlrev_b32_e32 v110, 16, v166
	v_and_b32_e32 v111, 0xffff0000, v166
	v_lshlrev_b32_e32 v104, 16, v167
	v_and_b32_e32 v105, 0xffff0000, v167
	v_lshlrev_b32_e32 v112, 16, v168
	v_and_b32_e32 v113, 0xffff0000, v168
	v_lshlrev_b32_e32 v106, 16, v169
	v_and_b32_e32 v107, 0xffff0000, v169
	v_pk_fma_f32 v[102:103], v[104:105], s[18:19], v[102:103] op_sel_hi:[1,0,1]
	v_pk_fma_f32 v[100:101], v[110:111], s[18:19], v[100:101] op_sel_hi:[1,0,1]
	v_pk_fma_f32 v[104:105], v[106:107], s[18:19], v[98:99] op_sel_hi:[1,0,1]
	v_pk_fma_f32 v[98:99], v[112:113], s[18:19], v[96:97] op_sel_hi:[1,0,1]
	v_cvt_pk_bf16_f32 v96, v100, v101
	v_cvt_pk_bf16_f32 v97, v102, v103
	v_cvt_pk_bf16_f32 v98, v98, v99
	v_cvt_pk_bf16_f32 v99, v104, v105
	v_lshl_add_u64 v[100:101], v[138:139], 0, s[16:17]
	global_store_dwordx4 v[108:109], v[96:99], off offset:256
	s_mov_b64 s[16:17], 0x18000
	s_waitcnt vmcnt(15)
	v_lshlrev_b32_e32 v104, 16, v170
	v_and_b32_e32 v105, 0xffff0000, v170
	v_lshlrev_b32_e32 v96, 16, v171
	v_and_b32_e32 v97, 0xffff0000, v171
	v_lshlrev_b32_e32 v106, 16, v172
	v_and_b32_e32 v107, 0xffff0000, v172
	v_lshlrev_b32_e32 v98, 16, v173
	v_and_b32_e32 v99, 0xffff0000, v173
	v_pk_fma_f32 v[94:95], v[96:97], s[18:19], v[94:95] op_sel_hi:[1,0,1]
	v_pk_fma_f32 v[92:93], v[104:105], s[18:19], v[92:93] op_sel_hi:[1,0,1]
	v_pk_fma_f32 v[96:97], v[98:99], s[18:19], v[90:91] op_sel_hi:[1,0,1]
	v_pk_fma_f32 v[90:91], v[106:107], s[18:19], v[88:89] op_sel_hi:[1,0,1]
	v_cvt_pk_bf16_f32 v88, v92, v93
	v_cvt_pk_bf16_f32 v89, v94, v95
	v_cvt_pk_bf16_f32 v90, v90, v91
	v_cvt_pk_bf16_f32 v91, v96, v97
	v_lshl_add_u64 v[92:93], s[42:43], 0, v[100:101]
	global_store_dwordx4 v[92:93], v[88:91], off
	s_waitcnt vmcnt(15)
	v_lshlrev_b32_e32 v94, 16, v174
	v_and_b32_e32 v95, 0xffff0000, v174
	v_lshlrev_b32_e32 v88, 16, v175
	v_and_b32_e32 v89, 0xffff0000, v175
	v_lshlrev_b32_e32 v96, 16, v176
	v_and_b32_e32 v97, 0xffff0000, v176
	v_lshlrev_b32_e32 v90, 16, v177
	v_and_b32_e32 v91, 0xffff0000, v177
	v_pk_fma_f32 v[86:87], v[88:89], s[18:19], v[86:87] op_sel_hi:[1,0,1]
	v_pk_fma_f32 v[84:85], v[94:95], s[18:19], v[84:85] op_sel_hi:[1,0,1]
	v_pk_fma_f32 v[88:89], v[90:91], s[18:19], v[82:83] op_sel_hi:[1,0,1]
	v_pk_fma_f32 v[82:83], v[96:97], s[18:19], v[80:81] op_sel_hi:[1,0,1]
	v_cvt_pk_bf16_f32 v80, v84, v85
	v_cvt_pk_bf16_f32 v81, v86, v87
	v_cvt_pk_bf16_f32 v82, v82, v83
	v_cvt_pk_bf16_f32 v83, v88, v89
	v_lshl_add_u64 v[84:85], v[138:139], 0, s[16:17]
	global_store_dwordx4 v[92:93], v[80:83], off offset:256
	s_mov_b64 s[16:17], 0x48000
	s_waitcnt vmcnt(15)
	v_lshlrev_b32_e32 v88, 16, v178
	v_and_b32_e32 v89, 0xffff0000, v178
	v_lshlrev_b32_e32 v80, 16, v179
	v_and_b32_e32 v81, 0xffff0000, v179
	v_lshlrev_b32_e32 v90, 16, v180
	v_and_b32_e32 v91, 0xffff0000, v180
	v_lshlrev_b32_e32 v82, 16, v181
	v_and_b32_e32 v83, 0xffff0000, v181
	v_pk_fma_f32 v[78:79], v[80:81], s[18:19], v[78:79] op_sel_hi:[1,0,1]
	v_pk_fma_f32 v[76:77], v[88:89], s[18:19], v[76:77] op_sel_hi:[1,0,1]
	v_pk_fma_f32 v[80:81], v[82:83], s[18:19], v[74:75] op_sel_hi:[1,0,1]
	v_pk_fma_f32 v[74:75], v[90:91], s[18:19], v[72:73] op_sel_hi:[1,0,1]
	v_cvt_pk_bf16_f32 v72, v76, v77
	v_cvt_pk_bf16_f32 v73, v78, v79
	v_cvt_pk_bf16_f32 v74, v74, v75
	v_cvt_pk_bf16_f32 v75, v80, v81
	v_lshl_add_u64 v[76:77], s[42:43], 0, v[84:85]
	global_store_dwordx4 v[76:77], v[72:75], off
	s_waitcnt vmcnt(15)
	v_lshlrev_b32_e32 v78, 16, v182
	v_and_b32_e32 v79, 0xffff0000, v182
	v_lshlrev_b32_e32 v72, 16, v183
	v_and_b32_e32 v73, 0xffff0000, v183
	v_lshlrev_b32_e32 v80, 16, v184
	v_and_b32_e32 v81, 0xffff0000, v184
	v_lshlrev_b32_e32 v74, 16, v185
	v_and_b32_e32 v75, 0xffff0000, v185
	v_pk_fma_f32 v[70:71], v[72:73], s[18:19], v[70:71] op_sel_hi:[1,0,1]
	v_pk_fma_f32 v[68:69], v[78:79], s[18:19], v[68:69] op_sel_hi:[1,0,1]
	v_pk_fma_f32 v[72:73], v[74:75], s[18:19], v[66:67] op_sel_hi:[1,0,1]
	v_pk_fma_f32 v[66:67], v[80:81], s[18:19], v[64:65] op_sel_hi:[1,0,1]
	v_cvt_pk_bf16_f32 v64, v68, v69
	v_cvt_pk_bf16_f32 v65, v70, v71
	v_cvt_pk_bf16_f32 v66, v66, v67
	v_cvt_pk_bf16_f32 v67, v72, v73
	v_lshl_add_u64 v[68:69], v[138:139], 0, s[26:27]
	global_store_dwordx4 v[76:77], v[64:67], off offset:256
	s_waitcnt vmcnt(15)
	v_lshlrev_b32_e32 v72, 16, v194
	v_and_b32_e32 v73, 0xffff0000, v194
	v_lshlrev_b32_e32 v64, 16, v195
	v_and_b32_e32 v65, 0xffff0000, v195
	v_lshlrev_b32_e32 v74, 16, v196
	v_and_b32_e32 v75, 0xffff0000, v196
	v_lshlrev_b32_e32 v66, 16, v197
	v_and_b32_e32 v67, 0xffff0000, v197
	v_pk_fma_f32 v[62:63], v[64:65], s[18:19], v[62:63] op_sel_hi:[1,0,1]
	v_pk_fma_f32 v[60:61], v[72:73], s[18:19], v[60:61] op_sel_hi:[1,0,1]
	v_pk_fma_f32 v[64:65], v[66:67], s[18:19], v[58:59] op_sel_hi:[1,0,1]
	v_pk_fma_f32 v[58:59], v[74:75], s[18:19], v[56:57] op_sel_hi:[1,0,1]
	v_cvt_pk_bf16_f32 v56, v60, v61
	v_cvt_pk_bf16_f32 v57, v62, v63
	v_cvt_pk_bf16_f32 v58, v58, v59
	v_cvt_pk_bf16_f32 v59, v64, v65
	v_lshl_add_u64 v[60:61], s[42:43], 0, v[68:69]
	global_store_dwordx4 v[60:61], v[56:59], off
	s_waitcnt vmcnt(15)
	v_lshlrev_b32_e32 v62, 16, v198
	v_and_b32_e32 v63, 0xffff0000, v198
	v_lshlrev_b32_e32 v56, 16, v199
	v_and_b32_e32 v57, 0xffff0000, v199
	v_lshlrev_b32_e32 v64, 16, v200
	v_and_b32_e32 v65, 0xffff0000, v200
	v_lshlrev_b32_e32 v58, 16, v201
	v_and_b32_e32 v59, 0xffff0000, v201
	v_pk_fma_f32 v[54:55], v[56:57], s[18:19], v[54:55] op_sel_hi:[1,0,1]
	v_pk_fma_f32 v[52:53], v[62:63], s[18:19], v[52:53] op_sel_hi:[1,0,1]
	v_pk_fma_f32 v[56:57], v[58:59], s[18:19], v[50:51] op_sel_hi:[1,0,1]
	v_pk_fma_f32 v[50:51], v[64:65], s[18:19], v[48:49] op_sel_hi:[1,0,1]
	v_cvt_pk_bf16_f32 v48, v52, v53
	v_cvt_pk_bf16_f32 v49, v54, v55
	v_cvt_pk_bf16_f32 v50, v50, v51
	v_cvt_pk_bf16_f32 v51, v56, v57
	v_lshl_add_u64 v[52:53], v[138:139], 0, s[16:17]
	global_store_dwordx4 v[60:61], v[48:51], off offset:256
	s_mov_b64 s[16:17], 0x50000
	s_waitcnt vmcnt(15)
	v_lshlrev_b32_e32 v56, 16, v202
	v_and_b32_e32 v57, 0xffff0000, v202
	v_lshlrev_b32_e32 v48, 16, v203
	v_and_b32_e32 v49, 0xffff0000, v203
	v_lshlrev_b32_e32 v58, 16, v204
	v_and_b32_e32 v59, 0xffff0000, v204
	v_lshlrev_b32_e32 v50, 16, v205
	v_and_b32_e32 v51, 0xffff0000, v205
	v_pk_fma_f32 v[46:47], v[48:49], s[18:19], v[46:47] op_sel_hi:[1,0,1]
	v_pk_fma_f32 v[44:45], v[56:57], s[18:19], v[44:45] op_sel_hi:[1,0,1]
	v_pk_fma_f32 v[48:49], v[50:51], s[18:19], v[42:43] op_sel_hi:[1,0,1]
	v_pk_fma_f32 v[42:43], v[58:59], s[18:19], v[40:41] op_sel_hi:[1,0,1]
	v_cvt_pk_bf16_f32 v40, v44, v45
	v_cvt_pk_bf16_f32 v41, v46, v47
	v_cvt_pk_bf16_f32 v42, v42, v43
	v_cvt_pk_bf16_f32 v43, v48, v49
	v_lshl_add_u64 v[44:45], s[42:43], 0, v[52:53]
	global_store_dwordx4 v[44:45], v[40:43], off
	s_waitcnt vmcnt(15)
	v_lshlrev_b32_e32 v46, 16, v206
	v_and_b32_e32 v47, 0xffff0000, v206
	v_lshlrev_b32_e32 v40, 16, v207
	v_and_b32_e32 v41, 0xffff0000, v207
	v_lshlrev_b32_e32 v48, 16, v208
	v_and_b32_e32 v49, 0xffff0000, v208
	v_lshlrev_b32_e32 v42, 16, v209
	v_and_b32_e32 v43, 0xffff0000, v209
	v_pk_fma_f32 v[38:39], v[40:41], s[18:19], v[38:39] op_sel_hi:[1,0,1]
	v_pk_fma_f32 v[36:37], v[46:47], s[18:19], v[36:37] op_sel_hi:[1,0,1]
	v_pk_fma_f32 v[40:41], v[42:43], s[18:19], v[34:35] op_sel_hi:[1,0,1]
	v_pk_fma_f32 v[34:35], v[48:49], s[18:19], v[32:33] op_sel_hi:[1,0,1]
	v_cvt_pk_bf16_f32 v32, v36, v37
	v_cvt_pk_bf16_f32 v33, v38, v39
	v_cvt_pk_bf16_f32 v34, v34, v35
	v_cvt_pk_bf16_f32 v35, v40, v41
	v_lshl_add_u64 v[36:37], v[138:139], 0, s[16:17]
	global_store_dwordx4 v[44:45], v[32:35], off offset:256
	s_mov_b64 s[16:17], 0x58000
	s_waitcnt vmcnt(15)
	v_lshlrev_b32_e32 v40, 16, v210
	v_and_b32_e32 v41, 0xffff0000, v210
	v_lshlrev_b32_e32 v32, 16, v211
	v_and_b32_e32 v33, 0xffff0000, v211
	v_lshlrev_b32_e32 v42, 16, v212
	v_and_b32_e32 v43, 0xffff0000, v212
	v_lshlrev_b32_e32 v34, 16, v213
	v_and_b32_e32 v35, 0xffff0000, v213
	v_pk_fma_f32 v[30:31], v[32:33], s[18:19], v[30:31] op_sel_hi:[1,0,1]
	v_pk_fma_f32 v[28:29], v[40:41], s[18:19], v[28:29] op_sel_hi:[1,0,1]
	v_pk_fma_f32 v[32:33], v[34:35], s[18:19], v[26:27] op_sel_hi:[1,0,1]
	v_pk_fma_f32 v[26:27], v[42:43], s[18:19], v[24:25] op_sel_hi:[1,0,1]
	v_cvt_pk_bf16_f32 v24, v28, v29
	v_cvt_pk_bf16_f32 v25, v30, v31
	v_cvt_pk_bf16_f32 v26, v26, v27
	v_cvt_pk_bf16_f32 v27, v32, v33
	v_lshl_add_u64 v[28:29], s[42:43], 0, v[36:37]
	global_store_dwordx4 v[28:29], v[24:27], off
	s_waitcnt vmcnt(15)
	v_lshlrev_b32_e32 v30, 16, v220
	v_and_b32_e32 v31, 0xffff0000, v220
	v_lshlrev_b32_e32 v24, 16, v221
	v_and_b32_e32 v25, 0xffff0000, v221
	v_lshlrev_b32_e32 v32, 16, v222
	v_and_b32_e32 v33, 0xffff0000, v222
	v_lshlrev_b32_e32 v26, 16, v223
	v_and_b32_e32 v27, 0xffff0000, v223
	v_pk_fma_f32 v[22:23], v[24:25], s[18:19], v[22:23] op_sel_hi:[1,0,1]
	v_pk_fma_f32 v[20:21], v[30:31], s[18:19], v[20:21] op_sel_hi:[1,0,1]
	v_pk_fma_f32 v[24:25], v[26:27], s[18:19], v[18:19] op_sel_hi:[1,0,1]
	v_pk_fma_f32 v[18:19], v[32:33], s[18:19], v[16:17] op_sel_hi:[1,0,1]
	v_cvt_pk_bf16_f32 v16, v20, v21
	v_cvt_pk_bf16_f32 v17, v22, v23
	v_cvt_pk_bf16_f32 v18, v18, v19
	v_cvt_pk_bf16_f32 v19, v24, v25
	v_lshl_add_u64 v[20:21], v[138:139], 0, s[16:17]
	global_store_dwordx4 v[28:29], v[16:19], off offset:256
	s_mov_b64 s[16:17], -1
	s_waitcnt vmcnt(15)
	v_lshlrev_b32_e32 v24, 16, v236
	v_and_b32_e32 v25, 0xffff0000, v236
	v_lshlrev_b32_e32 v16, 16, v237
	v_and_b32_e32 v17, 0xffff0000, v237
	v_lshlrev_b32_e32 v26, 16, v238
	v_and_b32_e32 v27, 0xffff0000, v238
	v_lshlrev_b32_e32 v18, 16, v239
	v_and_b32_e32 v19, 0xffff0000, v239
	v_pk_fma_f32 v[14:15], v[16:17], s[18:19], v[14:15] op_sel_hi:[1,0,1]
	v_pk_fma_f32 v[12:13], v[24:25], s[18:19], v[12:13] op_sel_hi:[1,0,1]
	v_pk_fma_f32 v[16:17], v[18:19], s[18:19], v[10:11] op_sel_hi:[1,0,1]
	v_pk_fma_f32 v[10:11], v[26:27], s[18:19], v[8:9] op_sel_hi:[1,0,1]
	v_cvt_pk_bf16_f32 v8, v12, v13
	v_cvt_pk_bf16_f32 v9, v14, v15
	v_cvt_pk_bf16_f32 v10, v10, v11
	v_cvt_pk_bf16_f32 v11, v16, v17
	v_lshl_add_u64 v[12:13], s[42:43], 0, v[20:21]
	global_store_dwordx4 v[12:13], v[8:11], off
	s_waitcnt vmcnt(15)
	v_lshlrev_b32_e32 v14, 16, v240
	v_and_b32_e32 v15, 0xffff0000, v240
	v_lshlrev_b32_e32 v8, 16, v241
	v_and_b32_e32 v9, 0xffff0000, v241
	v_lshlrev_b32_e32 v16, 16, v242
	v_and_b32_e32 v17, 0xffff0000, v242
	v_lshlrev_b32_e32 v10, 16, v243
	v_and_b32_e32 v11, 0xffff0000, v243
	v_pk_fma_f32 v[6:7], v[8:9], s[18:19], v[6:7] op_sel_hi:[1,0,1]
	v_pk_fma_f32 v[4:5], v[14:15], s[18:19], v[4:5] op_sel_hi:[1,0,1]
	v_pk_fma_f32 v[8:9], v[10:11], s[18:19], v[2:3] op_sel_hi:[1,0,1]
	v_pk_fma_f32 v[2:3], v[16:17], s[18:19], v[0:1] op_sel_hi:[1,0,1]
	v_cvt_pk_bf16_f32 v0, v4, v5
	v_cvt_pk_bf16_f32 v1, v6, v7
	v_cvt_pk_bf16_f32 v2, v2, v3
	v_cvt_pk_bf16_f32 v3, v8, v9
	global_store_dwordx4 v[12:13], v[0:3], off offset:256
	s_cbranch_vccnz .LBB0_350
	s_andn2_b64 vcc, exec, s[36:37]
	s_cbranch_vccnz .LBB0_349
	s_barrier
	s_branch .LBB0_349

.LBB0_1870:
	s_lshl_b32 s3, s77, 8
	v_mov_b32_e32 v0, v179
	v_mov_b32_e32 v1, v180
	s_add_i32 s3, s3, s67
	s_mov_b64 s[16:17], 0x4000
	v_add_u32_e32 v2, s3, v0
	s_lshl_b32 s3, s76, 8
	s_or_b32 s3, s3, s70
	v_ashrrev_i32_e32 v3, 31, v2
	v_lshl_add_u32 v4, v1, 3, s3
	v_lshl_add_u64 v[0:1], v[2:3], 2, s[46:47]
	global_load_dword v228, v[0:1], off
	global_load_dword v229, v[0:1], off offset:64
	global_load_dword v230, v[0:1], off offset:128
	global_load_dword v231, v[0:1], off offset:192
	global_load_dword v232, v[0:1], off offset:512
	global_load_dword v233, v[0:1], off offset:576
	global_load_dword v234, v[0:1], off offset:640
	global_load_dword v235, v[0:1], off offset:704
	v_lshlrev_b64 v[2:3], 10, v[2:3]
	v_ashrrev_i32_e32 v5, 31, v4
	v_lshl_add_u64 v[2:3], s[44:45], 0, v[2:3]
	v_lshl_add_u64 v[2:3], v[2:3], 0, v[4:5]
	s_movk_i32 s3, 0x4000
	s_mov_b64 s[82:83], 0x800
	s_waitcnt vmcnt(7)
	v_mul_f32_e32 v6, 0x3d800000, v228
	v_pk_mul_f32 v[10:11], v[156:157], v[6:7] op_sel_hi:[1,0]
	v_pk_mul_f32 v[8:9], v[158:159], v[6:7] op_sel_hi:[1,0]
	v_pk_mul_f32 v[12:13], v[154:155], v[6:7] op_sel_hi:[1,0]
	v_pk_mul_f32 v[14:15], v[152:153], v[6:7] op_sel_hi:[1,0]
	v_med3_f32 v7, v10, s15, v190
	v_med3_f32 v11, v11, s15, v190
	v_mov_b32_e32 v10, v189
	v_cvt_pk_fp8_f32 v10, v7, v11
	v_med3_f32 v7, v8, s15, v190
	v_med3_f32 v8, v9, s15, v190
	v_mov_b32_e32 v11, v189
	v_cvt_pk_fp8_f32 v10, v7, v8 op_sel:[0,0,1]
	v_med3_f32 v7, v14, s15, v190
	v_med3_f32 v8, v15, s15, v190
	v_cvt_pk_fp8_f32 v11, v7, v8
	v_med3_f32 v7, v12, s15, v190
	v_med3_f32 v8, v13, s15, v190
	v_pk_mul_f32 v[4:5], v[150:151], v[6:7] op_sel_hi:[1,0]
	v_cvt_pk_fp8_f32 v11, v7, v8 op_sel:[0,0,1]
	v_pk_mul_f32 v[8:9], v[148:149], v[6:7] op_sel_hi:[1,0]
	v_med3_f32 v4, v4, s15, v190
	v_med3_f32 v12, v8, s15, v190
	v_med3_f32 v9, v9, s15, v190
	v_mov_b32_e32 v8, v189
	v_cvt_pk_fp8_f32 v8, v12, v9
	global_store_dwordx2 v[2:3], v[10:11], off
	v_pk_mul_f32 v[10:11], v[146:147], v[6:7] op_sel_hi:[1,0]
	v_pk_mul_f32 v[6:7], v[144:145], v[6:7] op_sel_hi:[1,0]
	v_med3_f32 v5, v5, s15, v190
	v_cvt_pk_fp8_f32 v8, v4, v5 op_sel:[0,0,1]
	v_med3_f32 v4, v6, s15, v190
	v_med3_f32 v5, v7, s15, v190
	v_mov_b32_e32 v9, v189
	v_cvt_pk_fp8_f32 v9, v4, v5
	v_med3_f32 v4, v10, s15, v190
	v_med3_f32 v5, v11, s15, v190
	v_cvt_pk_fp8_f32 v9, v4, v5 op_sel:[0,0,1]
	global_store_dwordx2 v[2:3], v[8:9], off offset:128
	s_waitcnt vmcnt(8)
	v_mul_f32_e32 v4, 0x3d800000, v229
	v_pk_mul_f32 v[8:9], v[140:141], v[4:5] op_sel_hi:[1,0]
	v_pk_mul_f32 v[6:7], v[142:143], v[4:5] op_sel_hi:[1,0]
	v_pk_mul_f32 v[10:11], v[138:139], v[4:5] op_sel_hi:[1,0]
	v_pk_mul_f32 v[12:13], v[136:137], v[4:5] op_sel_hi:[1,0]
	v_med3_f32 v5, v8, s15, v190
	v_med3_f32 v9, v9, s15, v190
	v_mov_b32_e32 v8, v189
	v_cvt_pk_fp8_f32 v8, v5, v9
	v_med3_f32 v5, v6, s15, v190
	v_med3_f32 v6, v7, s15, v190
	v_mov_b32_e32 v9, v189
	v_cvt_pk_fp8_f32 v8, v5, v6 op_sel:[0,0,1]
	v_med3_f32 v5, v12, s15, v190
	v_med3_f32 v6, v13, s15, v190
	v_cvt_pk_fp8_f32 v9, v5, v6
	v_med3_f32 v5, v10, s15, v190
	v_med3_f32 v6, v11, s15, v190
	v_add_co_u32_e32 v10, vcc, s3, v2
	v_cvt_pk_fp8_f32 v9, v5, v6 op_sel:[0,0,1]
	s_nop 0
	v_addc_co_u32_e32 v11, vcc, 0, v3, vcc
	v_pk_mul_f32 v[12:13], v[130:131], v[4:5] op_sel_hi:[1,0]
	global_store_dwordx2 v[10:11], v[8:9], off
	v_pk_mul_f32 v[10:11], v[132:133], v[4:5] op_sel_hi:[1,0]
	v_pk_mul_f32 v[8:9], v[134:135], v[4:5] op_sel_hi:[1,0]
	v_pk_mul_f32 v[4:5], v[128:129], v[4:5] op_sel_hi:[1,0]
	v_med3_f32 v14, v10, s15, v190
	v_med3_f32 v11, v11, s15, v190
	v_mov_b32_e32 v10, v189
	v_cvt_pk_fp8_f32 v10, v14, v11
	v_med3_f32 v4, v4, s15, v190
	v_med3_f32 v5, v5, s15, v190
	v_mov_b32_e32 v11, v189
	v_cvt_pk_fp8_f32 v11, v4, v5
	v_med3_f32 v8, v8, s15, v190
	v_med3_f32 v9, v9, s15, v190
	v_med3_f32 v4, v12, s15, v190
	v_med3_f32 v5, v13, s15, v190
	v_cvt_pk_fp8_f32 v10, v8, v9 op_sel:[0,0,1]
	v_cvt_pk_fp8_f32 v11, v4, v5 op_sel:[0,0,1]
	v_lshl_add_u64 v[6:7], v[2:3], 0, s[16:17]
	s_mov_b64 s[16:17], 0x8000
	s_mov_b32 s3, 0xc000
	global_store_dwordx2 v[6:7], v[10:11], off offset:128
	s_waitcnt vmcnt(9)
	v_mul_f32_e32 v6, 0x3d800000, v230
	v_pk_mul_f32 v[8:9], v[124:125], v[6:7] op_sel_hi:[1,0]
	v_pk_mul_f32 v[4:5], v[126:127], v[6:7] op_sel_hi:[1,0]
	v_pk_mul_f32 v[10:11], v[122:123], v[6:7] op_sel_hi:[1,0]
	v_pk_mul_f32 v[12:13], v[120:121], v[6:7] op_sel_hi:[1,0]
	v_med3_f32 v7, v8, s15, v190
	v_med3_f32 v9, v9, s15, v190
	v_mov_b32_e32 v8, v189
	v_cvt_pk_fp8_f32 v8, v7, v9
	v_med3_f32 v4, v4, s15, v190
	v_med3_f32 v5, v5, s15, v190
	v_mov_b32_e32 v9, v189
	v_cvt_pk_fp8_f32 v8, v4, v5 op_sel:[0,0,1]
	v_med3_f32 v4, v12, s15, v190
	v_med3_f32 v5, v13, s15, v190
	v_cvt_pk_fp8_f32 v9, v4, v5
	v_med3_f32 v4, v10, s15, v190
	v_med3_f32 v5, v11, s15, v190
	v_add_co_u32_e32 v10, vcc, s87, v2
	v_cvt_pk_fp8_f32 v9, v4, v5 op_sel:[0,0,1]
	s_nop 0
	v_addc_co_u32_e32 v11, vcc, 0, v3, vcc
	v_pk_mul_f32 v[12:13], v[114:115], v[6:7] op_sel_hi:[1,0]
	global_store_dwordx2 v[10:11], v[8:9], off
	v_pk_mul_f32 v[10:11], v[116:117], v[6:7] op_sel_hi:[1,0]
	v_pk_mul_f32 v[8:9], v[118:119], v[6:7] op_sel_hi:[1,0]
	v_pk_mul_f32 v[6:7], v[112:113], v[6:7] op_sel_hi:[1,0]
	v_med3_f32 v14, v10, s15, v190
	v_med3_f32 v11, v11, s15, v190
	v_mov_b32_e32 v10, v189
	v_cvt_pk_fp8_f32 v10, v14, v11
	v_med3_f32 v6, v6, s15, v190
	v_med3_f32 v7, v7, s15, v190
	v_mov_b32_e32 v11, v189
	v_cvt_pk_fp8_f32 v11, v6, v7
	v_med3_f32 v8, v8, s15, v190
	v_med3_f32 v9, v9, s15, v190
	v_med3_f32 v6, v12, s15, v190
	v_med3_f32 v7, v13, s15, v190
	v_cvt_pk_fp8_f32 v10, v8, v9 op_sel:[0,0,1]
	v_cvt_pk_fp8_f32 v11, v6, v7 op_sel:[0,0,1]
	v_lshl_add_u64 v[4:5], v[2:3], 0, s[16:17]
	s_mov_b64 s[16:17], 0xc000
	global_store_dwordx2 v[4:5], v[10:11], off offset:128
	s_waitcnt vmcnt(10)
	v_mul_f32_e32 v4, 0x3d800000, v231
	v_pk_mul_f32 v[8:9], v[108:109], v[4:5] op_sel_hi:[1,0]
	v_pk_mul_f32 v[6:7], v[110:111], v[4:5] op_sel_hi:[1,0]
	v_pk_mul_f32 v[10:11], v[106:107], v[4:5] op_sel_hi:[1,0]
	v_pk_mul_f32 v[12:13], v[104:105], v[4:5] op_sel_hi:[1,0]
	v_med3_f32 v5, v8, s15, v190
	v_med3_f32 v9, v9, s15, v190
	v_mov_b32_e32 v8, v189
	v_cvt_pk_fp8_f32 v8, v5, v9
	v_med3_f32 v5, v6, s15, v190
	v_med3_f32 v6, v7, s15, v190
	v_mov_b32_e32 v9, v189
	v_cvt_pk_fp8_f32 v8, v5, v6 op_sel:[0,0,1]
	v_med3_f32 v5, v12, s15, v190
	v_med3_f32 v6, v13, s15, v190
	v_cvt_pk_fp8_f32 v9, v5, v6
	v_med3_f32 v5, v10, s15, v190
	v_med3_f32 v6, v11, s15, v190
	v_add_co_u32_e32 v10, vcc, s3, v2
	v_cvt_pk_fp8_f32 v9, v5, v6 op_sel:[0,0,1]
	s_nop 0
	v_addc_co_u32_e32 v11, vcc, 0, v3, vcc
	v_pk_mul_f32 v[12:13], v[98:99], v[4:5] op_sel_hi:[1,0]
	global_store_dwordx2 v[10:11], v[8:9], off
	v_pk_mul_f32 v[10:11], v[100:101], v[4:5] op_sel_hi:[1,0]
	v_pk_mul_f32 v[8:9], v[102:103], v[4:5] op_sel_hi:[1,0]
	v_pk_mul_f32 v[4:5], v[96:97], v[4:5] op_sel_hi:[1,0]
	v_med3_f32 v14, v10, s15, v190
	v_med3_f32 v11, v11, s15, v190
	v_mov_b32_e32 v10, v189
	v_cvt_pk_fp8_f32 v10, v14, v11
	v_med3_f32 v4, v4, s15, v190
	v_med3_f32 v5, v5, s15, v190
	v_mov_b32_e32 v11, v189
	v_cvt_pk_fp8_f32 v11, v4, v5
	v_med3_f32 v8, v8, s15, v190
	v_med3_f32 v9, v9, s15, v190
	v_med3_f32 v4, v12, s15, v190
	v_med3_f32 v5, v13, s15, v190
	v_cvt_pk_fp8_f32 v10, v8, v9 op_sel:[0,0,1]
	v_cvt_pk_fp8_f32 v11, v4, v5 op_sel:[0,0,1]
	v_lshl_add_u64 v[6:7], v[2:3], 0, s[16:17]
	s_mov_b32 s3, 0x20000
	s_mov_b64 s[16:17], 0x20000
	global_store_dwordx2 v[6:7], v[10:11], off offset:128
	s_waitcnt vmcnt(11)
	v_mul_f32_e32 v4, 0x3d800000, v232
	v_pk_mul_f32 v[8:9], v[92:93], v[4:5] op_sel_hi:[1,0]
	v_pk_mul_f32 v[6:7], v[94:95], v[4:5] op_sel_hi:[1,0]
	v_pk_mul_f32 v[10:11], v[90:91], v[4:5] op_sel_hi:[1,0]
	v_pk_mul_f32 v[12:13], v[88:89], v[4:5] op_sel_hi:[1,0]
	v_med3_f32 v5, v8, s15, v190
	v_med3_f32 v9, v9, s15, v190
	v_mov_b32_e32 v8, v189
	v_cvt_pk_fp8_f32 v8, v5, v9
	v_med3_f32 v5, v6, s15, v190
	v_med3_f32 v6, v7, s15, v190
	v_mov_b32_e32 v9, v189
	v_cvt_pk_fp8_f32 v8, v5, v6 op_sel:[0,0,1]
	v_med3_f32 v5, v12, s15, v190
	v_med3_f32 v6, v13, s15, v190
	v_cvt_pk_fp8_f32 v9, v5, v6
	v_med3_f32 v5, v10, s15, v190
	v_med3_f32 v6, v11, s15, v190
	v_add_co_u32_e32 v10, vcc, s3, v2
	v_cvt_pk_fp8_f32 v9, v5, v6 op_sel:[0,0,1]
	s_nop 0
	v_addc_co_u32_e32 v11, vcc, 0, v3, vcc
	v_pk_mul_f32 v[12:13], v[82:83], v[4:5] op_sel_hi:[1,0]
	global_store_dwordx2 v[10:11], v[8:9], off
	v_pk_mul_f32 v[10:11], v[84:85], v[4:5] op_sel_hi:[1,0]
	v_pk_mul_f32 v[8:9], v[86:87], v[4:5] op_sel_hi:[1,0]
	v_pk_mul_f32 v[4:5], v[80:81], v[4:5] op_sel_hi:[1,0]
	v_med3_f32 v14, v10, s15, v190
	v_med3_f32 v11, v11, s15, v190
	v_mov_b32_e32 v10, v189
	v_cvt_pk_fp8_f32 v10, v14, v11
	v_med3_f32 v4, v4, s15, v190
	v_med3_f32 v5, v5, s15, v190
	v_mov_b32_e32 v11, v189
	v_cvt_pk_fp8_f32 v11, v4, v5
	v_med3_f32 v8, v8, s15, v190
	v_med3_f32 v9, v9, s15, v190
	v_med3_f32 v4, v12, s15, v190
	v_med3_f32 v5, v13, s15, v190
	v_cvt_pk_fp8_f32 v10, v8, v9 op_sel:[0,0,1]
	v_cvt_pk_fp8_f32 v11, v4, v5 op_sel:[0,0,1]
	v_lshl_add_u64 v[6:7], v[2:3], 0, s[16:17]
	s_mov_b32 s3, 0x24000
	s_mov_b64 s[16:17], 0x24000
	global_store_dwordx2 v[6:7], v[10:11], off offset:128
	s_waitcnt vmcnt(12)
	v_mul_f32_e32 v4, 0x3d800000, v233
	v_pk_mul_f32 v[8:9], v[76:77], v[4:5] op_sel_hi:[1,0]
	v_pk_mul_f32 v[6:7], v[78:79], v[4:5] op_sel_hi:[1,0]
	v_pk_mul_f32 v[10:11], v[74:75], v[4:5] op_sel_hi:[1,0]
	v_pk_mul_f32 v[12:13], v[72:73], v[4:5] op_sel_hi:[1,0]
	v_med3_f32 v5, v8, s15, v190
	v_med3_f32 v9, v9, s15, v190
	v_mov_b32_e32 v8, v189
	v_cvt_pk_fp8_f32 v8, v5, v9
	v_med3_f32 v5, v6, s15, v190
	v_med3_f32 v6, v7, s15, v190
	v_mov_b32_e32 v9, v189
	v_cvt_pk_fp8_f32 v8, v5, v6 op_sel:[0,0,1]
	v_med3_f32 v5, v12, s15, v190
	v_med3_f32 v6, v13, s15, v190
	v_cvt_pk_fp8_f32 v9, v5, v6
	v_med3_f32 v5, v10, s15, v190
	v_med3_f32 v6, v11, s15, v190
	v_add_co_u32_e32 v10, vcc, s3, v2
	v_cvt_pk_fp8_f32 v9, v5, v6 op_sel:[0,0,1]
	s_nop 0
	v_addc_co_u32_e32 v11, vcc, 0, v3, vcc
	v_pk_mul_f32 v[12:13], v[66:67], v[4:5] op_sel_hi:[1,0]
	global_store_dwordx2 v[10:11], v[8:9], off
	v_pk_mul_f32 v[10:11], v[68:69], v[4:5] op_sel_hi:[1,0]
	v_pk_mul_f32 v[8:9], v[70:71], v[4:5] op_sel_hi:[1,0]
	v_pk_mul_f32 v[4:5], v[64:65], v[4:5] op_sel_hi:[1,0]
	v_med3_f32 v14, v10, s15, v190
	v_med3_f32 v11, v11, s15, v190
	v_mov_b32_e32 v10, v189
	v_cvt_pk_fp8_f32 v10, v14, v11
	v_med3_f32 v4, v4, s15, v190
	v_med3_f32 v5, v5, s15, v190
	v_mov_b32_e32 v11, v189
	v_cvt_pk_fp8_f32 v11, v4, v5
	v_med3_f32 v8, v8, s15, v190
	v_med3_f32 v9, v9, s15, v190
	v_med3_f32 v4, v12, s15, v190
	v_med3_f32 v5, v13, s15, v190
	v_cvt_pk_fp8_f32 v10, v8, v9 op_sel:[0,0,1]
	v_cvt_pk_fp8_f32 v11, v4, v5 op_sel:[0,0,1]
	v_lshl_add_u64 v[6:7], v[2:3], 0, s[16:17]
	s_mov_b32 s3, 0x28000
	s_mov_b64 s[16:17], 0x28000
	global_store_dwordx2 v[6:7], v[10:11], off offset:128
	s_waitcnt vmcnt(13)
	v_mul_f32_e32 v4, 0x3d800000, v234
	v_pk_mul_f32 v[8:9], v[60:61], v[4:5] op_sel_hi:[1,0]
	v_pk_mul_f32 v[6:7], v[62:63], v[4:5] op_sel_hi:[1,0]
	v_pk_mul_f32 v[10:11], v[58:59], v[4:5] op_sel_hi:[1,0]
	v_pk_mul_f32 v[12:13], v[56:57], v[4:5] op_sel_hi:[1,0]
	v_med3_f32 v5, v8, s15, v190
	v_med3_f32 v9, v9, s15, v190
	v_mov_b32_e32 v8, v189
	v_cvt_pk_fp8_f32 v8, v5, v9
	v_med3_f32 v5, v6, s15, v190
	v_med3_f32 v6, v7, s15, v190
	v_mov_b32_e32 v9, v189
	v_cvt_pk_fp8_f32 v8, v5, v6 op_sel:[0,0,1]
	v_med3_f32 v5, v12, s15, v190
	v_med3_f32 v6, v13, s15, v190
	v_cvt_pk_fp8_f32 v9, v5, v6
	v_med3_f32 v5, v10, s15, v190
	v_med3_f32 v6, v11, s15, v190
	v_add_co_u32_e32 v10, vcc, s3, v2
	v_cvt_pk_fp8_f32 v9, v5, v6 op_sel:[0,0,1]
	s_nop 0
	v_addc_co_u32_e32 v11, vcc, 0, v3, vcc
	v_pk_mul_f32 v[12:13], v[50:51], v[4:5] op_sel_hi:[1,0]
	global_store_dwordx2 v[10:11], v[8:9], off
	v_pk_mul_f32 v[10:11], v[52:53], v[4:5] op_sel_hi:[1,0]
	v_pk_mul_f32 v[8:9], v[54:55], v[4:5] op_sel_hi:[1,0]
	v_pk_mul_f32 v[4:5], v[48:49], v[4:5] op_sel_hi:[1,0]
	v_med3_f32 v14, v10, s15, v190
	v_med3_f32 v11, v11, s15, v190
	v_mov_b32_e32 v10, v189
	v_cvt_pk_fp8_f32 v10, v14, v11
	v_med3_f32 v4, v4, s15, v190
	v_med3_f32 v5, v5, s15, v190
	v_mov_b32_e32 v11, v189
	v_cvt_pk_fp8_f32 v11, v4, v5
	v_med3_f32 v8, v8, s15, v190
	v_med3_f32 v9, v9, s15, v190
	v_med3_f32 v4, v12, s15, v190
	v_med3_f32 v5, v13, s15, v190
	v_cvt_pk_fp8_f32 v10, v8, v9 op_sel:[0,0,1]
	v_cvt_pk_fp8_f32 v11, v4, v5 op_sel:[0,0,1]
	v_lshl_add_u64 v[6:7], v[2:3], 0, s[16:17]
	s_mov_b64 s[16:17], 0x2c000
	s_mov_b32 s3, 0x2c000
	global_store_dwordx2 v[6:7], v[10:11], off offset:128
	s_waitcnt vmcnt(14)
	v_mul_f32_e32 v0, 0x3d800000, v235
	v_pk_mul_f32 v[6:7], v[44:45], v[0:1] op_sel_hi:[1,0]
	v_pk_mul_f32 v[4:5], v[46:47], v[0:1] op_sel_hi:[1,0]
	v_pk_mul_f32 v[8:9], v[42:43], v[0:1] op_sel_hi:[1,0]
	v_pk_mul_f32 v[10:11], v[40:41], v[0:1] op_sel_hi:[1,0]
	v_med3_f32 v1, v6, s15, v190
	v_med3_f32 v7, v7, s15, v190
	v_mov_b32_e32 v6, v189
	v_cvt_pk_fp8_f32 v6, v1, v7
	v_med3_f32 v1, v4, s15, v190
	v_med3_f32 v4, v5, s15, v190
	v_mov_b32_e32 v7, v189
	v_cvt_pk_fp8_f32 v6, v1, v4 op_sel:[0,0,1]
	v_med3_f32 v1, v10, s15, v190
	v_med3_f32 v4, v11, s15, v190
	v_cvt_pk_fp8_f32 v7, v1, v4
	v_med3_f32 v1, v8, s15, v190
	v_med3_f32 v4, v9, s15, v190
	v_pk_mul_f32 v[8:9], v[34:35], v[0:1] op_sel_hi:[1,0]
	v_cvt_pk_fp8_f32 v7, v1, v4 op_sel:[0,0,1]
	v_lshl_add_u64 v[4:5], v[2:3], 0, s[16:17]
	v_add_co_u32_e32 v2, vcc, s3, v2
	s_mov_b64 s[16:17], -1
	s_nop 0
	v_addc_co_u32_e32 v3, vcc, 0, v3, vcc
	global_store_dwordx2 v[2:3], v[6:7], off
	v_pk_mul_f32 v[6:7], v[36:37], v[0:1] op_sel_hi:[1,0]
	v_pk_mul_f32 v[2:3], v[38:39], v[0:1] op_sel_hi:[1,0]
	v_pk_mul_f32 v[0:1], v[32:33], v[0:1] op_sel_hi:[1,0]
	v_med3_f32 v10, v6, s15, v190
	v_med3_f32 v7, v7, s15, v190
	v_mov_b32_e32 v6, v189
	v_cvt_pk_fp8_f32 v6, v10, v7
	v_med3_f32 v0, v0, s15, v190
	v_med3_f32 v1, v1, s15, v190
	v_mov_b32_e32 v7, v189
	v_cvt_pk_fp8_f32 v7, v0, v1
	v_med3_f32 v2, v2, s15, v190
	v_med3_f32 v3, v3, s15, v190
	v_med3_f32 v0, v8, s15, v190
	v_med3_f32 v1, v9, s15, v190
	v_cvt_pk_fp8_f32 v6, v2, v3 op_sel:[0,0,1]
	v_cvt_pk_fp8_f32 v7, v0, v1 op_sel:[0,0,1]
	s_and_b64 vcc, exec, s[38:39]
	global_store_dwordx2 v[4:5], v[6:7], off offset:128
	s_cbranch_vccnz .LBB0_1861
	s_andn2_b64 vcc, exec, s[42:43]
	s_cbranch_vccnz .LBB0_1860
	s_barrier
	s_branch .LBB0_1860
